# MLA loop: V^T fragment reads as ds_read_b64 pairs (2 LDS cycles each) instead of ds_read2_b64 (8 cycles each)
# baseline (speedup 1.0000x reference)
; #define LAS __attribute__((address_space(3)))
; template <bool SUM> __device__ __forceinline__ bool softmax_tile(f32x16& pa, f32x16& pb, float& m, float& l, f32x16& o0, f32x16& o1, bool first) {
;     ...
;     else { int im = max(imax16(pa), imax16(pb));
;         const auto rr = __builtin_amdgcn_permlane32_swap((unsigned)im, (unsigned)im, false, false); im = max((int)rr[0], (int)rr[1]); rm = __int_as_float(im); }
;     bool moved = false;
;     if (first || __any(rm > 8.0f)) {
;         asm volatile("" ::: "memory");
;         const float dl = first ? rm : fmaxf(rm, 0.f); m += dl; moved = true;
;         if (!first) { const float f = __builtin_amdgcn_exp2f(-dl); l *= f;
; #pragma unroll
;             for (int r = 0; r < 16; ++r) { o0[r] *= f; o1[r] *= f; } }
; #pragma unroll
;         for (int r = 0; r < 16; ++r) { pa[r] -= dl; pb[r] -= dl; }
;     ...
;             const LAS unsigned char* vb = bb + KB + r32 * VP + 8 * hi;
; #pragma unroll
;             for (int dh = 0; dh < 2; ++dh) {
;                 bf16x8 vf[4];
; #pragma unroll
;                 for (int ks = 0; ks < 4; ++ks) {
;                     const u32x2 v0 = *(const LAS u32x2*)(vb + dh * 32 * VP + 32 * ks), v1 = *(const LAS u32x2*)(vb + dh * 32 * VP + 32 * ks + 16);
;                     const u32x4 vv = {v0.x, v0.y, v1.x, v1.y}; vf[ks] = __builtin_bit_cast(bf16x8, vv); }
.LBB0_264:
	s_waitcnt lgkmcnt(10)
	v_mfma_f32_32x32x16_bf16 v[68:83], v[172:175], v[108:111], v[68:83]
	s_waitcnt lgkmcnt(4)
	v_mfma_f32_32x32x16_bf16 v[84:99], v[152:155], v[108:111], v[84:99]
	v_mfma_f32_32x32x16_bf16 v[68:83], v[168:171], v[112:115], v[68:83]
	s_waitcnt lgkmcnt(3)
	v_mfma_f32_32x32x16_bf16 v[84:99], v[148:151], v[112:115], v[84:99]
	v_mfma_f32_32x32x16_bf16 v[68:83], v[164:167], v[116:119], v[68:83]
	s_waitcnt lgkmcnt(2)
	v_mfma_f32_32x32x16_bf16 v[84:99], v[144:147], v[116:119], v[84:99]
	v_mfma_f32_32x32x16_bf16 v[68:83], v[160:163], v[124:127], v[68:83]
	s_waitcnt lgkmcnt(1)
	v_mfma_f32_32x32x16_bf16 v[84:99], v[140:143], v[124:127], v[84:99]
	v_mfma_f32_32x32x16_bf16 v[68:83], v[156:159], v[120:123], v[68:83]
	s_waitcnt lgkmcnt(0)
	v_mfma_f32_32x32x16_bf16 v[84:99], v[136:139], v[120:123], v[84:99]
	s_bitcmp1_b32 s12, 0
	s_cselect_b32 s12, 0x5700, 0
	s_addk_i32 s12, 0x100
	v_add3_u32 v180, s12, v200, v201
	s_waitcnt vmcnt(0)
	ds_write_b128 v180, v[132:135]
	s_and_saveexec_b64 s[46:47], s[44:45]
	v_add3_u32 v180, s12, v203, v202
	ds_write_b128 v180, v[100:103] offset:128
	s_or_b64 exec, exec, s[46:47]
	s_mov_b64 s[18:19], 0x1000
	v_add_u32_e32 v180, s12, v210
	v_lshl_add_u64 v[194:195], v[194:195], 0, s[18:19]
	s_mov_b64 s[18:19], 0x10000
	v_add3_u32 v180, v180, v201, s13
	v_lshl_add_u64 v[0:1], v[0:1], 0, s[18:19]
	v_lshl_add_u64 v[196:197], v[196:197], 0, s[8:9]
	ds_write2_b64 v180, v[128:129], v[130:131] offset1:1
	v_add3_u32 v180, s15, v206, v199
	v_add_u32_e32 v181, 0x3000, v180
	v_add_u32_e32 v180, 0x4000, v180
	ds_read_b64 v[144:145], v181 offset:1024
	ds_read_b64 v[146:147], v181 offset:1040
	ds_read_b64 v[160:161], v180 offset:1280
	ds_read_b64 v[162:163], v180 offset:1296
	ds_read_b64 v[148:149], v181 offset:1056
	ds_read_b64 v[150:151], v181 offset:1072
	ds_read_b64 v[164:165], v180 offset:1312
	ds_read_b64 v[166:167], v180 offset:1328
	ds_read_b64 v[152:153], v181 offset:1088
	ds_read_b64 v[154:155], v181 offset:1104
	ds_read_b64 v[168:169], v180 offset:1344
	ds_read_b64 v[170:171], v180 offset:1360
	ds_read_b64 v[156:157], v181 offset:1120
	ds_read_b64 v[158:159], v181 offset:1136
	ds_read_b64 v[172:173], v180 offset:1376
	ds_read_b64 v[174:175], v180 offset:1392
	v_max3_i32 v136, v68, v69, v70
	v_max3_i32 v137, v71, v72, v73
	v_max3_i32 v138, v74, v75, v76
	v_max3_i32 v139, v77, v78, v79
	v_max3_i32 v140, v80, v81, v82
	v_max3_i32 v136, v136, v137, v138
	v_max3_i32 v137, v139, v140, v83
	v_max_i32_e32 v138, v84, v85
	v_max3_i32 v139, v87, v88, v89
	v_max3_i32 v141, v93, v94, v95
	v_max3_i32 v142, v96, v97, v98
	v_max3_i32 v140, v90, v91, v92
	v_max3_i32 v138, v138, v86, v139
	v_max3_i32 v139, v141, v142, v99
	v_max3_i32 v138, v138, v140, v139
	v_max3_i32 v136, v136, v137, v138
	v_mov_b32_e32 v137, v136
	s_nop 1
	v_permlane32_swap_b32_e32 v136, v137
	v_max_i32_e32 v136, v136, v137
	v_cmp_lt_f32_e32 vcc, s17, v136
	s_cmp_lg_u64 vcc, 0
	s_cselect_b64 s[46:47], -1, 0
	s_cbranch_vccz .LBB0_272
	v_max_f32_e32 v136, v136, v136
	v_max_f32_e32 v138, 0, v136
	v_exp_f32_e64 v140, -v138
	v_add_f32_e32 v207, v207, v138
	v_pk_add_f32 v[68:69], v[68:69], v[138:139] op_sel_hi:[1,0] neg_lo:[0,1] neg_hi:[0,1]
	v_mul_f32_e32 v136, v208, v140
	v_pk_mul_f32 v[34:35], v[34:35], v[140:141] op_sel_hi:[1,0]
	v_pk_mul_f32 v[32:33], v[32:33], v[140:141] op_sel_hi:[1,0]
	v_pk_mul_f32 v[30:31], v[30:31], v[140:141] op_sel_hi:[1,0]
	v_pk_mul_f32 v[28:29], v[28:29], v[140:141] op_sel_hi:[1,0]
	v_pk_mul_f32 v[26:27], v[26:27], v[140:141] op_sel_hi:[1,0]
	v_pk_mul_f32 v[24:25], v[24:25], v[140:141] op_sel_hi:[1,0]
	v_pk_mul_f32 v[22:23], v[22:23], v[140:141] op_sel_hi:[1,0]
	v_pk_mul_f32 v[20:21], v[20:21], v[140:141] op_sel_hi:[1,0]
	v_pk_mul_f32 v[18:19], v[18:19], v[140:141] op_sel_hi:[1,0]
	v_pk_mul_f32 v[16:17], v[16:17], v[140:141] op_sel_hi:[1,0]
	v_pk_mul_f32 v[14:15], v[14:15], v[140:141] op_sel_hi:[1,0]
	v_pk_mul_f32 v[12:13], v[12:13], v[140:141] op_sel_hi:[1,0]
	v_pk_mul_f32 v[10:11], v[10:11], v[140:141] op_sel_hi:[1,0]
	v_pk_mul_f32 v[8:9], v[8:9], v[140:141] op_sel_hi:[1,0]
	v_pk_mul_f32 v[6:7], v[6:7], v[140:141] op_sel_hi:[1,0]
	v_pk_mul_f32 v[4:5], v[4:5], v[140:141] op_sel_hi:[1,0]
	v_pk_add_f32 v[84:85], v[84:85], v[138:139] op_sel_hi:[1,0] neg_lo:[0,1] neg_hi:[0,1]
	v_pk_add_f32 v[70:71], v[70:71], v[138:139] op_sel_hi:[1,0] neg_lo:[0,1] neg_hi:[0,1]
	v_pk_add_f32 v[86:87], v[86:87], v[138:139] op_sel_hi:[1,0] neg_lo:[0,1] neg_hi:[0,1]
	v_pk_add_f32 v[72:73], v[72:73], v[138:139] op_sel_hi:[1,0] neg_lo:[0,1] neg_hi:[0,1]
	v_pk_add_f32 v[88:89], v[88:89], v[138:139] op_sel_hi:[1,0] neg_lo:[0,1] neg_hi:[0,1]
	v_pk_add_f32 v[74:75], v[74:75], v[138:139] op_sel_hi:[1,0] neg_lo:[0,1] neg_hi:[0,1]
	v_pk_add_f32 v[90:91], v[90:91], v[138:139] op_sel_hi:[1,0] neg_lo:[0,1] neg_hi:[0,1]
	v_pk_add_f32 v[76:77], v[76:77], v[138:139] op_sel_hi:[1,0] neg_lo:[0,1] neg_hi:[0,1]
	v_pk_add_f32 v[92:93], v[92:93], v[138:139] op_sel_hi:[1,0] neg_lo:[0,1] neg_hi:[0,1]
	v_pk_add_f32 v[78:79], v[78:79], v[138:139] op_sel_hi:[1,0] neg_lo:[0,1] neg_hi:[0,1]
	v_pk_add_f32 v[94:95], v[94:95], v[138:139] op_sel_hi:[1,0] neg_lo:[0,1] neg_hi:[0,1]
	v_pk_add_f32 v[80:81], v[80:81], v[138:139] op_sel_hi:[1,0] neg_lo:[0,1] neg_hi:[0,1]
	v_pk_add_f32 v[96:97], v[96:97], v[138:139] op_sel_hi:[1,0] neg_lo:[0,1] neg_hi:[0,1]
	v_pk_add_f32 v[82:83], v[82:83], v[138:139] op_sel_hi:[1,0] neg_lo:[0,1] neg_hi:[0,1]
	v_pk_add_f32 v[98:99], v[98:99], v[138:139] op_sel_hi:[1,0] neg_lo:[0,1] neg_hi:[0,1]
	s_andn2_b64 vcc, exec, s[46:47]
	s_cbranch_vccnz .LBB0_267

; #define LAS __attribute__((address_space(3)))
; #define MFMA32(a, b, c) __builtin_amdgcn_mfma_f32_32x32x16_bf16((a), (b), (c), 0, 0, 0)
; template <bool SUM> __device__ __forceinline__ bool softmax_tile(f32x16& pa, f32x16& pb, float& m, float& l, f32x16& o0, f32x16& o1, bool first) {
;     ...
; #pragma unroll
;     for (int r = 0; r < 16; ++r) { pa[r] = __builtin_amdgcn_exp2f(pa[r]); pb[r] = __builtin_amdgcn_exp2f(pb[r]); }
;     ...
;                 for (int ks = 0; ks < 4; ++ks) pf[mp][ks] = pack_frag(p[ks >> 1], ks & 1);
;             }
;             const LAS unsigned char* vb = bb + KB + r32 * VP + 8 * hi;
; #pragma unroll
;             for (int dh = 0; dh < 2; ++dh) {
;                 bf16x8 vf[4];
; #pragma unroll
;                 for (int ks = 0; ks < 4; ++ks) {
;                     const u32x2 v0 = *(const LAS u32x2*)(vb + dh * 32 * VP + 32 * ks), v1 = *(const LAS u32x2*)(vb + dh * 32 * VP + 32 * ks + 16);
;                     const u32x4 vv = {v0.x, v0.y, v1.x, v1.y}; vf[ks] = __builtin_bit_cast(bf16x8, vv); }
;                 __builtin_amdgcn_sched_barrier(0);
; #pragma unroll
;                 for (int ks = 0; ks < 4; ++ks)
; #pragma unroll
;                     for (int mp = 0; mp < NM; ++mp) o[mp][dh] = MFMA32(vf[ks], pf[mp][ks], o[mp][dh]);
;                 __builtin_amdgcn_sched_barrier(0);
;             }
;             if constexpr (MODE == 0) {
;                 const u32x4 o1 = {0x3f803f80u, 0x3f803f80u, 0x3f803f80u, 0x3f803f80u}; const bf16x8 ones = __builtin_bit_cast(bf16x8, o1);
; #pragma unroll
;                 for (int ks = 0; ks < 4; ++ks) lsum = MFMA32(ones, pf[0][ks], lsum);
.LBB0_267:
	v_exp_f32_e32 v68, v68
	v_exp_f32_e32 v69, v69
	v_exp_f32_e32 v70, v70
	v_exp_f32_e32 v71, v71
	v_exp_f32_e32 v72, v72
	v_exp_f32_e32 v73, v73
	v_exp_f32_e32 v74, v74
	v_exp_f32_e32 v75, v75
	v_cvt_pk_bf16_f32 v68, v68, v69
	v_cvt_pk_bf16_f32 v69, v70, v71
	v_cvt_pk_bf16_f32 v70, v72, v73
	v_cvt_pk_bf16_f32 v71, v74, v75
	s_mov_b32 s70, s68
	s_mov_b32 s71, s68
	s_mov_b32 s69, s68
	v_mov_b64_e32 v[178:179], s[70:71]
	v_mov_b64_e32 v[176:177], s[68:69]
	v_mov_b32_e32 v208, v136
	s_waitcnt lgkmcnt(12)
	v_mfma_f32_32x32x16_bf16 v[4:19], v[144:147], v[68:71], v[4:19]
	v_exp_f32_e32 v76, v76
	v_exp_f32_e32 v77, v77
	v_exp_f32_e32 v78, v78
	v_mfma_f32_32x32x16_bf16 v[20:35], v[160:163], v[68:71], v[20:35]
	v_exp_f32_e32 v79, v79
	v_exp_f32_e32 v80, v80
	v_exp_f32_e32 v81, v81
	v_mfma_f32_32x32x16_bf16 v[36:51], v[176:179], v[68:71], v[36:51]
	v_exp_f32_e32 v82, v82
	v_exp_f32_e32 v83, v83
	v_cvt_pk_bf16_f32 v72, v76, v77
	v_cvt_pk_bf16_f32 v73, v78, v79
	v_cvt_pk_bf16_f32 v74, v80, v81
	v_cvt_pk_bf16_f32 v75, v82, v83
	s_waitcnt lgkmcnt(8)
	s_nop 0
	v_mfma_f32_32x32x16_bf16 v[4:19], v[148:151], v[72:75], v[4:19]
	v_exp_f32_e32 v84, v84
	v_exp_f32_e32 v85, v85
	v_exp_f32_e32 v86, v86
	v_mfma_f32_32x32x16_bf16 v[20:35], v[164:167], v[72:75], v[20:35]
	v_exp_f32_e32 v87, v87
	v_exp_f32_e32 v88, v88
	v_exp_f32_e32 v89, v89
	v_mfma_f32_32x32x16_bf16 v[36:51], v[176:179], v[72:75], v[36:51]
	v_exp_f32_e32 v90, v90
	v_exp_f32_e32 v91, v91
	v_cvt_pk_bf16_f32 v76, v84, v85
	v_cvt_pk_bf16_f32 v77, v86, v87
	v_cvt_pk_bf16_f32 v78, v88, v89
	v_cvt_pk_bf16_f32 v79, v90, v91
	s_waitcnt lgkmcnt(4)
	s_nop 0
	v_mfma_f32_32x32x16_bf16 v[4:19], v[152:155], v[76:79], v[4:19]
	v_exp_f32_e32 v92, v92
	v_exp_f32_e32 v93, v93
	v_exp_f32_e32 v94, v94
	v_mfma_f32_32x32x16_bf16 v[20:35], v[168:171], v[76:79], v[20:35]
	v_exp_f32_e32 v95, v95
	v_exp_f32_e32 v96, v96
	v_exp_f32_e32 v97, v97
	v_mfma_f32_32x32x16_bf16 v[36:51], v[176:179], v[76:79], v[36:51]
	v_exp_f32_e32 v98, v98
	v_exp_f32_e32 v99, v99
	v_cvt_pk_bf16_f32 v80, v92, v93
	v_cvt_pk_bf16_f32 v81, v94, v95
	v_cvt_pk_bf16_f32 v82, v96, v97
	v_cvt_pk_bf16_f32 v83, v98, v99
	s_waitcnt lgkmcnt(0)
	s_nop 0
	v_mfma_f32_32x32x16_bf16 v[4:19], v[156:159], v[80:83], v[4:19]
	v_mfma_f32_32x32x16_bf16 v[20:35], v[172:175], v[80:83], v[20:35]
	v_mfma_f32_32x32x16_bf16 v[36:51], v[176:179], v[80:83], v[36:51]
	s_cmp_lg_u32 s5, s11
	s_branch .Lmla_join
